# MLA deferred-max test moved after exp: OR of the packed bf16 P words, exponent-msb mask (p>=2 <=> score exceeds reference by 8, reference biased by 7); on trigger the tile's S is recomputed and the ex
# speedup vs baseline: 1.0278x; 1.0173x over previous
; template <bool MLA> __device__ __forceinline__ void attn_unit(const AttnP& P, int b, int hh, int qb, LAS char* lds) {
;     ...
;     const int qlo = q0 + wid * 32, qm = qlo + r32 - 4 * hi;
;     bf16x8 qr[NQF];
;     const size_t qrow = rowbase + qlo + r32;
;     if constexpr (MLA) {
; #pragma unroll
;         for (int d0 = 0; d0 < 8; ++d0) qr[d0] = *(const bf16x8*)(P.QN + qrow * 2048 + hh * 128 + d0 * 16 + hi * 8);
; #pragma unroll
;         for (int d0 = 0; d0 < 4; ++d0) qr[8 + d0] = *(const bf16x8*)(P.QR + qrow * 1024 + hh * 64 + d0 * 16 + hi * 8);
;     } else {
; #pragma unroll
;         for (int d0 = 0; d0 < 4; ++d0) qr[d0] = *(const bf16x8*)(P.QS + qrow * 2048 + hh * 64 + d0 * 16 + hi * 8);
;         if (tid < 128) bias_l[tid] = P.rel[(int)T5B[tid] * 32 + hh] * (1.0f / SCALE);
;     }
;     bf16x8 sk0, sv0;
;     const int sr8 = tid >> 3, ch8 = tid & 7;
;     const bf16_t* Kg; const bf16_t* Vg; const bf16_t* Rg = nullptr;
;     unsigned okA = 0, okB = 0, orp = 0, ovA = 0, ovB = 0;
;     if constexpr (MLA) {
;         Kg = P.KN + rowbase * 2048 + hh * 128; Vg = P.V + rowbase * 2048 + hh * 128; Rg = P.KR + rowbase * 64;
;         { const int rA = 4 * wid + (lane >> 4), rB = rA + 32, cp = lane & 15; okA = (unsigned)(rA * 2048 + ((cp ^ (rA & 7)) << 3)); okB = (unsigned)(rB * 2048 + ((cp ^ (rB & 7)) << 3)); }
;         { const int rr = 8 * wid + (lane >> 3), cp = lane & 7; orp = (unsigned)(rr * 64 + ((cp ^ (rr & 7)) << 3)); }
;         { const int stA = 2 * wid + (lane >> 5), stB = stA + 16; const int kl = (lane & 31) >> 2, c8 = 8 * (lane & 3);
;           const int kkA = (stA >> 2) * 8 + kl, kkB = (stB >> 2) * 8 + kl;
;           const int kA = (kkA & ~0xC) | ((kkA & 4) << 1) | ((kkA & 8) >> 1), kB = (kkB & ~0xC) | ((kkB & 4) << 1) | ((kkB & 8) >> 1);
;           ovA = (unsigned)(kA * 2048 + 32 * (stA & 3) + c8); ovB = (unsigned)(kB * 2048 + 32 * (stB & 3) + c8); }
;     } else { Kg = P.KS + (rowbase + sr8) * 256 + (hh >> 3) * 64 + ch8 * 8; Vg = P.VS + (rowbase + sr8) * 256 + (hh >> 3) * 64 + ch8 * 8; }
;     const int kws = KSWZ64(sr8, ch8), vst0 = v_st<NCB>(sr8, ch8 * 8);
;     ...
;     float m_reg = MLA ? 0.f : P.sinks[hh] * (1.0f / SCALE), l_reg = MLA ? 0.f : 1.f;
;     f32x16 o[NCB];
; #pragma unroll
;     for (int d = 0; d < NCB; ++d) o[d] = f32x16{};
;     const int vb0 = (int)(uintptr_t)V_lds + v_rd_base(lane);
.Lm16_qb_ok:
	s_lshr_b32 s36, s28, 5
	s_and_b32 s63, s36, 15
	s_lshr_b32 s64, s36, 4
	s_lshl_b32 s40, s33, 2
	s_add_u32 s40, s40, 4
	s_lshl_b32 s43, s33, 8
	s_lshl_b32 s36, s4, 5
	s_add_u32 s43, s43, s36
	s_lshl_b32 s36, s64, 14
	s_add_u32 s36, s36, s43
	s_lshl_b32 s37, s36, 12
	s_lshl_b32 s59, s63, 8
	s_add_u32 s37, s37, s59
	s_add_u32 s66, s6, s37
	s_addc_u32 s67, s7, 0
	s_lshl_b32 s37, s36, 11
	s_lshl_b32 s59, s63, 7
	s_add_u32 s37, s37, s59
	s_add_u32 s68, s8, s37
	s_addc_u32 s69, s9, 0
	s_lshl_b32 s37, s64, 26
	s_lshl_b32 s59, s63, 8
	s_add_u32 s37, s37, s59
	s_add_u32 s46, s12, s37
	s_addc_u32 s47, s13, 0
	s_add_u32 s48, s16, s37
	s_addc_u32 s49, s17, 0
	s_lshl_b32 s37, s64, 21
	s_add_u32 s50, s14, s37
	s_addc_u32 s51, s15, 0
	global_load_dwordx4 v[66:69], v237, s[66:67] offset:0
	global_load_dwordx4 v[70:73], v237, s[66:67] offset:64
	global_load_dwordx4 v[74:77], v237, s[66:67] offset:128
	global_load_dwordx4 v[78:81], v237, s[66:67] offset:192
	global_load_dwordx4 v[82:85], v239, s[68:69] offset:0
	global_load_dwordx4 v[86:89], v239, s[68:69] offset:64
	global_load_dwordx4 v[90:93], v238, s[66:67] offset:0
	global_load_dwordx4 v[94:97], v238, s[66:67] offset:64
	global_load_dwordx4 v[98:101], v238, s[66:67] offset:128
	global_load_dwordx4 v[102:105], v238, s[66:67] offset:192
	global_load_dwordx4 v[106:109], v240, s[68:69] offset:0
	global_load_dwordx4 v[110:113], v240, s[68:69] offset:64
	s_mov_b32 s70, 0x8000
	s_mov_b32 s71, 0
	s_add_i32 s36, s5, s70
	s_mov_b32 m0, s36
	s_nop 0
	global_load_lds_dwordx4 v232, s[46:47]
	s_add_i32 m0, s36, 0x2000
	s_nop 0
	global_load_lds_dwordx4 v233, s[46:47]
	s_add_i32 m0, s36, 0x4000
	s_nop 0
	global_load_lds_dwordx4 v234, s[50:51]
	s_add_i32 s36, s5, s71
	s_mov_b32 m0, s36
	s_nop 0
	global_load_lds_dwordx4 v235, s[48:49]
	s_add_i32 m0, s36, 0x2000
	s_nop 0
	global_load_lds_dwordx4 v236, s[48:49]
	s_add_u32 s46, s46, 0x40000
	s_addc_u32 s47, s47, 0
	s_add_u32 s48, s48, 0x40000
	s_addc_u32 s49, s49, 0
	s_add_u32 s50, s50, 0x2000
	s_addc_u32 s51, s51, 0
	v_mov_b32_e32 v2, 0
	v_mov_b32_e32 v3, 0
	v_mov_b32_e32 v4, 0
	v_mov_b32_e32 v5, 0
	v_mov_b32_e32 v6, 0
	v_mov_b32_e32 v7, 0
	v_mov_b32_e32 v8, 0
	v_mov_b32_e32 v9, 0
	v_mov_b32_e32 v10, 0
	v_mov_b32_e32 v11, 0
	v_mov_b32_e32 v12, 0
	v_mov_b32_e32 v13, 0
	v_mov_b32_e32 v14, 0
	v_mov_b32_e32 v15, 0
	v_mov_b32_e32 v16, 0
	v_mov_b32_e32 v17, 0
	v_mov_b32_e32 v18, 0
	v_mov_b32_e32 v19, 0
	v_mov_b32_e32 v20, 0
	v_mov_b32_e32 v21, 0
	v_mov_b32_e32 v22, 0
	v_mov_b32_e32 v23, 0
	v_mov_b32_e32 v24, 0
	v_mov_b32_e32 v25, 0
	v_mov_b32_e32 v26, 0
	v_mov_b32_e32 v27, 0
	v_mov_b32_e32 v28, 0
	v_mov_b32_e32 v29, 0
	v_mov_b32_e32 v30, 0
	v_mov_b32_e32 v31, 0
	v_mov_b32_e32 v32, 0
	v_mov_b32_e32 v33, 0
	v_mov_b32_e32 v34, 0
	v_mov_b32_e32 v35, 0
	v_mov_b32_e32 v36, 0
	v_mov_b32_e32 v37, 0
	v_mov_b32_e32 v38, 0
	v_mov_b32_e32 v39, 0
	v_mov_b32_e32 v40, 0
	v_mov_b32_e32 v41, 0
	v_mov_b32_e32 v42, 0
	v_mov_b32_e32 v43, 0
	v_mov_b32_e32 v44, 0
	v_mov_b32_e32 v45, 0
	v_mov_b32_e32 v46, 0
	v_mov_b32_e32 v47, 0
	v_mov_b32_e32 v48, 0
	v_mov_b32_e32 v49, 0
	v_mov_b32_e32 v50, 0
	v_mov_b32_e32 v51, 0
	v_mov_b32_e32 v52, 0
	v_mov_b32_e32 v53, 0
	v_mov_b32_e32 v54, 0
	v_mov_b32_e32 v55, 0
	v_mov_b32_e32 v56, 0
	v_mov_b32_e32 v57, 0
	v_mov_b32_e32 v58, 0
	v_mov_b32_e32 v59, 0
	v_mov_b32_e32 v60, 0
	v_mov_b32_e32 v61, 0
	v_mov_b32_e32 v62, 0
	v_mov_b32_e32 v63, 0
	v_mov_b32_e32 v64, 0
	v_mov_b32_e32 v65, 0
	v_mov_b32_e32 v218, 0
	v_mov_b32_e32 v146, 0
	v_mov_b32_e32 v154, 0x3f803f80
	v_mov_b32_e32 v147, 0
	v_mov_b32_e32 v155, 0x3f803f80
	v_mov_b32_e32 v148, 0
	v_mov_b32_e32 v156, 0x3f803f80
	v_mov_b32_e32 v149, 0
	v_mov_b32_e32 v157, 0x3f803f80
	v_mov_b32_e32 v208, 0xc0e00000
	v_mov_b32_e32 v209, 0xc0e00000
	v_mov_b32_e32 v210, 0xc0e00000
	v_mov_b32_e32 v211, 0xc0e00000
	v_mov_b32_e32 v219, 0
	v_mov_b32_e32 v150, 0
	v_mov_b32_e32 v154, 0x3f803f80
	v_mov_b32_e32 v151, 0
	v_mov_b32_e32 v155, 0x3f803f80
	v_mov_b32_e32 v152, 0
	v_mov_b32_e32 v156, 0x3f803f80
	v_mov_b32_e32 v153, 0
	v_mov_b32_e32 v157, 0x3f803f80
	v_mov_b32_e32 v212, 0xc0e00000
	v_mov_b32_e32 v213, 0xc0e00000
	v_mov_b32_e32 v214, 0xc0e00000
	v_mov_b32_e32 v215, 0xc0e00000
	s_mov_b32 s41, 0
	s_mov_b32 s42, 0
	s_waitcnt vmcnt(0)
	s_barrier

; #define WLK(n) do { asm volatile("s_waitcnt lgkmcnt(" #n ")" ::: "memory"); SBAR(); } while (0)
; #define RDN(S, dd, off) do { const int a_ = rb + (((dd) * 32 + h16) ^ sw); KRD(S##0, a_, off); KRD(S##1, a_, 8192 + (off)); } while (0)
; #define RDR(S, ks) do { const int a_ = rr + (((((ks) * 2 + hi)) ^ (r32 & 7)) << 4); KRD(S##0, a_, 0); KRD(S##1, a_, 4096); } while (0)
; __device__ __forceinline__ void partialSM_pre(f32x16& p0, f32x16& p1, float& m_reg, float& alpha) {
;     ...
;     if (__builtin_expect(__all(pmax <= THR2), 1)) { alpha = 1.f; }
;     else { const float d = fmaxf(pmax, 0.f); m_reg += d; alpha = __builtin_amdgcn_exp2f(-d);
; #pragma unroll
;         for (int r = 0; r < 16; ++r) { p0[r] -= d; p1[r] -= d; } }
; #pragma unroll
;     for (int r = 0; r < 16; ++r) p0[r] = __builtin_amdgcn_exp2f(p0[r]);
; }
; __device__ __forceinline__ void finishSM(f32x16& p0, f32x16& p1, float alpha, float& l_reg, bf16x8& pa0, bf16x8& pa1, bf16x8& pa2, bf16x8& pa3) {
; #pragma unroll
;     for (int r = 0; r < 16; ++r) p1[r] = __builtin_amdgcn_exp2f(p1[r]);
;     float ps = 0;
; #pragma unroll
;     for (int r = 0; r < 16; ++r) ps += p0[r];
; #pragma unroll
;     for (int r = 0; r < 16; ++r) ps += p1[r];
;     { auto rr = __builtin_amdgcn_permlane32_swap(__float_as_uint(ps), __float_as_uint(ps), false, false);
;       ps = __uint_as_float(rr[0]) + __uint_as_float(rr[1]); }
;     l_reg = l_reg * alpha + ps;
;     ...
;     PK4(p0, 0, pa0); PK4(p0, 8, pa1); PK4(p1, 0, pa2); PK4(p1, 8, pa3);
; __device__ __forceinline__ void qk_mla(f32x16& p0, f32x16& p1, int kaddr, int r32, int hi, const bf16x8* qr) {
;     const int rb = kaddr + r32 * 256, sw = (r32 & 7) << 4, h16 = hi * 16;
;     const int rr = kaddr + 16384 + r32 * 128;
;     ...
;     bf16x8 A0, A1, B0, B1;
;     RDN(A, 0, 0); RDN(B, 1, 0);
;     WLK(2); MM1(A, 0); RDN(A, 2, 0);
;     WLK(2); MM1(B, 1); RDN(B, 3, 0);
;     WLK(2); MM1(A, 2); RDN(A, 0, 128);
;     WLK(2); MM1(B, 3); RDN(B, 1, 128);
;     WLK(2); MM1(A, 4); RDN(A, 2, 128);
;     WLK(2); MM1(B, 5); RDN(B, 3, 128);
;     WLK(2); MM1(A, 6); RDR(A, 0);
;     WLK(2); MM1(B, 7); RDR(B, 1);
;     WLK(2); MM1(A, 8); RDR(A, 2);
;     WLK(2); MM1(B, 9); RDR(B, 3);
;     WLK(2); MM1(A, 10);
;     WLK(0); MM1(B, 11);
.Lm16_nomask:
	v_exp_f32_e32 v114, v114
	v_exp_f32_e32 v115, v115
	v_exp_f32_e32 v116, v116
	v_exp_f32_e32 v117, v117
	v_exp_f32_e32 v118, v118
	v_exp_f32_e32 v119, v119
	v_exp_f32_e32 v120, v120
	v_exp_f32_e32 v121, v121
	v_exp_f32_e32 v122, v122
	v_exp_f32_e32 v123, v123
	v_exp_f32_e32 v124, v124
	v_exp_f32_e32 v125, v125
	v_exp_f32_e32 v126, v126
	v_exp_f32_e32 v127, v127
	v_exp_f32_e32 v128, v128
	v_exp_f32_e32 v129, v129
	v_exp_f32_e32 v130, v130
	v_exp_f32_e32 v131, v131
	v_exp_f32_e32 v132, v132
	v_exp_f32_e32 v133, v133
	v_exp_f32_e32 v134, v134
	v_exp_f32_e32 v135, v135
	v_exp_f32_e32 v136, v136
	v_exp_f32_e32 v137, v137
	v_exp_f32_e32 v138, v138
	v_exp_f32_e32 v139, v139
	v_exp_f32_e32 v140, v140
	v_exp_f32_e32 v141, v141
	v_exp_f32_e32 v142, v142
	v_exp_f32_e32 v143, v143
	v_exp_f32_e32 v144, v144
	v_exp_f32_e32 v145, v145
	v_cvt_pk_bf16_f32 v164, v114, v115
	v_cvt_pk_bf16_f32 v165, v116, v117
	v_cvt_pk_bf16_f32 v166, v122, v123
	v_cvt_pk_bf16_f32 v167, v124, v125
	v_cvt_pk_bf16_f32 v168, v130, v131
	v_cvt_pk_bf16_f32 v169, v132, v133
	v_cvt_pk_bf16_f32 v170, v138, v139
	v_cvt_pk_bf16_f32 v171, v140, v141
	v_cvt_pk_bf16_f32 v172, v118, v119
	v_cvt_pk_bf16_f32 v173, v120, v121
	v_cvt_pk_bf16_f32 v174, v126, v127
	v_cvt_pk_bf16_f32 v175, v128, v129
	v_cvt_pk_bf16_f32 v176, v134, v135
	v_cvt_pk_bf16_f32 v177, v136, v137
	v_cvt_pk_bf16_f32 v178, v142, v143
	v_cvt_pk_bf16_f32 v179, v144, v145
	v_or3_b32 v220, v164, v165, v166
	v_or3_b32 v220, v220, v167, v168
	v_or3_b32 v220, v220, v169, v170
	v_or3_b32 v220, v220, v171, v172
	v_or3_b32 v220, v220, v173, v174
	v_or3_b32 v220, v220, v175, v176
	v_or3_b32 v220, v220, v177, v178
	v_or_b32_e32 v220, v220, v179
	v_and_b32_e32 v220, 0x40004000, v220
	v_cmp_eq_u32_e32 vcc, 0, v220
	s_cmp_eq_u64 vcc, exec
	s_cbranch_scc1 .Lm16_pv
	ds_read_b128 v[180:183], v228 offset:0
	ds_read_b128 v[184:187], v228 offset:2048
	ds_read_b128 v[188:191], v228 offset:4096
	ds_read_b128 v[192:195], v228 offset:6144
	s_waitcnt lgkmcnt(3)
	v_mfma_f32_16x16x32_bf16 v[114:117], v[180:183], v[66:69], v[208:211]
	v_mfma_f32_16x16x32_bf16 v[118:121], v[180:183], v[90:93], v[212:215]
	ds_read_b128 v[180:183], v229 offset:0
	s_waitcnt lgkmcnt(3)
	v_mfma_f32_16x16x32_bf16 v[122:125], v[184:187], v[66:69], v[208:211]
	v_mfma_f32_16x16x32_bf16 v[126:129], v[184:187], v[90:93], v[212:215]
	ds_read_b128 v[184:187], v229 offset:2048
	s_waitcnt lgkmcnt(3)
	v_mfma_f32_16x16x32_bf16 v[130:133], v[188:191], v[66:69], v[208:211]
	v_mfma_f32_16x16x32_bf16 v[134:137], v[188:191], v[90:93], v[212:215]
	ds_read_b128 v[188:191], v229 offset:4096
	s_waitcnt lgkmcnt(3)
	v_mfma_f32_16x16x32_bf16 v[138:141], v[192:195], v[66:69], v[208:211]
	v_mfma_f32_16x16x32_bf16 v[142:145], v[192:195], v[90:93], v[212:215]
	ds_read_b128 v[192:195], v229 offset:6144
	s_waitcnt lgkmcnt(3)
	v_mfma_f32_16x16x32_bf16 v[114:117], v[180:183], v[70:73], v[114:117]
	v_mfma_f32_16x16x32_bf16 v[118:121], v[180:183], v[94:97], v[118:121]
	ds_read_b128 v[180:183], v228 offset:8192
	s_waitcnt lgkmcnt(3)
	v_mfma_f32_16x16x32_bf16 v[122:125], v[184:187], v[70:73], v[122:125]
	v_mfma_f32_16x16x32_bf16 v[126:129], v[184:187], v[94:97], v[126:129]
	ds_read_b128 v[184:187], v228 offset:10240
	s_waitcnt lgkmcnt(3)
	v_mfma_f32_16x16x32_bf16 v[130:133], v[188:191], v[70:73], v[130:133]
	v_mfma_f32_16x16x32_bf16 v[134:137], v[188:191], v[94:97], v[134:137]
	ds_read_b128 v[188:191], v228 offset:12288
	s_waitcnt lgkmcnt(3)
	v_mfma_f32_16x16x32_bf16 v[138:141], v[192:195], v[70:73], v[138:141]
	v_mfma_f32_16x16x32_bf16 v[142:145], v[192:195], v[94:97], v[142:145]
	ds_read_b128 v[192:195], v228 offset:14336
	s_waitcnt lgkmcnt(3)
	v_mfma_f32_16x16x32_bf16 v[114:117], v[180:183], v[74:77], v[114:117]
	v_mfma_f32_16x16x32_bf16 v[118:121], v[180:183], v[98:101], v[118:121]
	ds_read_b128 v[180:183], v229 offset:8192
	s_waitcnt lgkmcnt(3)
	v_mfma_f32_16x16x32_bf16 v[122:125], v[184:187], v[74:77], v[122:125]
	v_mfma_f32_16x16x32_bf16 v[126:129], v[184:187], v[98:101], v[126:129]
	ds_read_b128 v[184:187], v229 offset:10240
	s_waitcnt lgkmcnt(3)
	v_mfma_f32_16x16x32_bf16 v[130:133], v[188:191], v[74:77], v[130:133]
	v_mfma_f32_16x16x32_bf16 v[134:137], v[188:191], v[98:101], v[134:137]
	ds_read_b128 v[188:191], v229 offset:12288
	s_waitcnt lgkmcnt(3)
	v_mfma_f32_16x16x32_bf16 v[138:141], v[192:195], v[74:77], v[138:141]
	v_mfma_f32_16x16x32_bf16 v[142:145], v[192:195], v[98:101], v[142:145]
	ds_read_b128 v[192:195], v229 offset:14336
	s_waitcnt lgkmcnt(3)
	v_mfma_f32_16x16x32_bf16 v[114:117], v[180:183], v[78:81], v[114:117]
	v_mfma_f32_16x16x32_bf16 v[118:121], v[180:183], v[102:105], v[118:121]
	ds_read_b128 v[180:183], v228 offset:16384
	s_waitcnt lgkmcnt(3)
	v_mfma_f32_16x16x32_bf16 v[122:125], v[184:187], v[78:81], v[122:125]
	v_mfma_f32_16x16x32_bf16 v[126:129], v[184:187], v[102:105], v[126:129]
	ds_read_b128 v[184:187], v228 offset:18432
	s_waitcnt lgkmcnt(3)
	v_mfma_f32_16x16x32_bf16 v[130:133], v[188:191], v[78:81], v[130:133]
	v_mfma_f32_16x16x32_bf16 v[134:137], v[188:191], v[102:105], v[134:137]
	ds_read_b128 v[188:191], v228 offset:20480
	s_waitcnt lgkmcnt(3)
	v_mfma_f32_16x16x32_bf16 v[138:141], v[192:195], v[78:81], v[138:141]
	v_mfma_f32_16x16x32_bf16 v[142:145], v[192:195], v[102:105], v[142:145]
	ds_read_b128 v[192:195], v228 offset:22528
	s_waitcnt lgkmcnt(3)
	v_mfma_f32_16x16x32_bf16 v[114:117], v[180:183], v[82:85], v[114:117]
	v_mfma_f32_16x16x32_bf16 v[118:121], v[180:183], v[106:109], v[118:121]
	ds_read_b128 v[180:183], v229 offset:16384
	s_waitcnt lgkmcnt(3)
	v_mfma_f32_16x16x32_bf16 v[122:125], v[184:187], v[82:85], v[122:125]
	v_mfma_f32_16x16x32_bf16 v[126:129], v[184:187], v[106:109], v[126:129]
	ds_read_b128 v[184:187], v229 offset:18432
	s_waitcnt lgkmcnt(3)
	v_mfma_f32_16x16x32_bf16 v[130:133], v[188:191], v[82:85], v[130:133]
	v_mfma_f32_16x16x32_bf16 v[134:137], v[188:191], v[106:109], v[134:137]
	ds_read_b128 v[188:191], v229 offset:20480
	s_waitcnt lgkmcnt(3)
	v_mfma_f32_16x16x32_bf16 v[138:141], v[192:195], v[82:85], v[138:141]
	v_mfma_f32_16x16x32_bf16 v[142:145], v[192:195], v[106:109], v[142:145]
	ds_read_b128 v[192:195], v229 offset:22528
	s_waitcnt lgkmcnt(3)
	v_mfma_f32_16x16x32_bf16 v[114:117], v[180:183], v[86:89], v[114:117]
	v_mfma_f32_16x16x32_bf16 v[118:121], v[180:183], v[110:113], v[118:121]
	s_waitcnt lgkmcnt(2)
	v_mfma_f32_16x16x32_bf16 v[122:125], v[184:187], v[86:89], v[122:125]
	v_mfma_f32_16x16x32_bf16 v[126:129], v[184:187], v[110:113], v[126:129]
	s_waitcnt lgkmcnt(1)
	v_mfma_f32_16x16x32_bf16 v[130:133], v[188:191], v[86:89], v[130:133]
	v_mfma_f32_16x16x32_bf16 v[134:137], v[188:191], v[110:113], v[134:137]
	s_waitcnt lgkmcnt(0)
	v_mfma_f32_16x16x32_bf16 v[138:141], v[192:195], v[86:89], v[138:141]
	v_mfma_f32_16x16x32_bf16 v[142:145], v[192:195], v[110:113], v[142:145]
	s_nop 7
	s_add_u32 s36, s42, 63
	s_cmp_gt_u32 s36, s43
	s_cbranch_scc0 .Lm16_nomask_s
; __device__ __forceinline__ void mask_tile(f32x16& p0, f32x16& p1, int dq, unsigned W) {
;     const float NEG = -__builtin_inff();
; #pragma unroll
;     for (int r = 0; r < 16; ++r) { const int c = (r & 3) + 8 * (r >> 2);
;         if ((unsigned)(dq - c) >= W) p0[r] = NEG;
;         if ((unsigned)(dq - c - 32) >= W) p1[r] = NEG; }
; }
; __device__ __forceinline__ void partialSM_pre(f32x16& p0, f32x16& p1, float& m_reg, float& alpha) {
;     constexpr float THR2 = THR * 1.4426950408889634f;
;     float pmax = p0[0];
; #pragma unroll
;     for (int r = 1; r < 16; ++r) pmax = fmaxf(pmax, p0[r]);
; #pragma unroll
;     for (int r = 0; r < 16; ++r) pmax = fmaxf(pmax, p1[r]);
;     { auto rr = __builtin_amdgcn_permlane32_swap(__float_as_uint(pmax), __float_as_uint(pmax), false, false);
;       pmax = fmaxf(__uint_as_float(rr[0]), __uint_as_float(rr[1])); }
;     if (__builtin_expect(__all(pmax <= THR2), 1)) { alpha = 1.f; }
;     else { const float d = fmaxf(pmax, 0.f); m_reg += d; alpha = __builtin_amdgcn_exp2f(-d);
; #pragma unroll
;         for (int r = 0; r < 16; ++r) { p0[r] -= d; p1[r] -= d; } }
	s_sub_u32 s36, s43, s42
	v_add_u32_e32 v244, s36, v243
	v_cmp_gt_i32_e32 vcc, 0, v244
	s_nop 1
	v_cndmask_b32_e32 v114, v114, v245, vcc
	v_cmp_gt_i32_e32 vcc, 1, v244
	s_nop 1
	v_cndmask_b32_e32 v115, v115, v245, vcc
	v_cmp_gt_i32_e32 vcc, 2, v244
	s_nop 1
	v_cndmask_b32_e32 v116, v116, v245, vcc
	v_cmp_gt_i32_e32 vcc, 3, v244
	s_nop 1
	v_cndmask_b32_e32 v117, v117, v245, vcc
	v_cmp_gt_i32_e32 vcc, -16, v244
	s_nop 1
	v_cndmask_b32_e32 v118, v118, v245, vcc
	v_cmp_gt_i32_e32 vcc, -15, v244
	s_nop 1
	v_cndmask_b32_e32 v119, v119, v245, vcc
	v_cmp_gt_i32_e32 vcc, -14, v244
	s_nop 1
	v_cndmask_b32_e32 v120, v120, v245, vcc
	v_cmp_gt_i32_e32 vcc, -13, v244
	s_nop 1
	v_cndmask_b32_e32 v121, v121, v245, vcc
	v_cmp_gt_i32_e32 vcc, 16, v244
	s_nop 1
	v_cndmask_b32_e32 v122, v122, v245, vcc
	v_cmp_gt_i32_e32 vcc, 17, v244
	s_nop 1
	v_cndmask_b32_e32 v123, v123, v245, vcc
	v_cmp_gt_i32_e32 vcc, 18, v244
	s_nop 1
	v_cndmask_b32_e32 v124, v124, v245, vcc
	v_cmp_gt_i32_e32 vcc, 19, v244
	s_nop 1
	v_cndmask_b32_e32 v125, v125, v245, vcc
	v_cmp_gt_i32_e32 vcc, 0, v244
	s_nop 1
	v_cndmask_b32_e32 v126, v126, v245, vcc
	v_cmp_gt_i32_e32 vcc, 1, v244
	s_nop 1
	v_cndmask_b32_e32 v127, v127, v245, vcc
	v_cmp_gt_i32_e32 vcc, 2, v244
	s_nop 1
	v_cndmask_b32_e32 v128, v128, v245, vcc
	v_cmp_gt_i32_e32 vcc, 3, v244
	s_nop 1
	v_cndmask_b32_e32 v129, v129, v245, vcc
	v_cmp_gt_i32_e32 vcc, 32, v244
	s_nop 1
	v_cndmask_b32_e32 v130, v130, v245, vcc
	v_cmp_gt_i32_e32 vcc, 33, v244
	s_nop 1
	v_cndmask_b32_e32 v131, v131, v245, vcc
	v_cmp_gt_i32_e32 vcc, 34, v244
	s_nop 1
	v_cndmask_b32_e32 v132, v132, v245, vcc
	v_cmp_gt_i32_e32 vcc, 35, v244
	s_nop 1
	v_cndmask_b32_e32 v133, v133, v245, vcc
	v_cmp_gt_i32_e32 vcc, 16, v244
	s_nop 1
	v_cndmask_b32_e32 v134, v134, v245, vcc
	v_cmp_gt_i32_e32 vcc, 17, v244
	s_nop 1
	v_cndmask_b32_e32 v135, v135, v245, vcc
	v_cmp_gt_i32_e32 vcc, 18, v244
	s_nop 1
	v_cndmask_b32_e32 v136, v136, v245, vcc
	v_cmp_gt_i32_e32 vcc, 19, v244
	s_nop 1
	v_cndmask_b32_e32 v137, v137, v245, vcc
	v_cmp_gt_i32_e32 vcc, 48, v244
	s_nop 1
	v_cndmask_b32_e32 v138, v138, v245, vcc
	v_cmp_gt_i32_e32 vcc, 49, v244
	s_nop 1
	v_cndmask_b32_e32 v139, v139, v245, vcc
	v_cmp_gt_i32_e32 vcc, 50, v244
	s_nop 1
	v_cndmask_b32_e32 v140, v140, v245, vcc
	v_cmp_gt_i32_e32 vcc, 51, v244
	s_nop 1
	v_cndmask_b32_e32 v141, v141, v245, vcc
	v_cmp_gt_i32_e32 vcc, 32, v244
	s_nop 1
	v_cndmask_b32_e32 v142, v142, v245, vcc
	v_cmp_gt_i32_e32 vcc, 33, v244
	s_nop 1
	v_cndmask_b32_e32 v143, v143, v245, vcc
	v_cmp_gt_i32_e32 vcc, 34, v244
	s_nop 1
	v_cndmask_b32_e32 v144, v144, v245, vcc
	v_cmp_gt_i32_e32 vcc, 35, v244
	s_nop 1
	v_cndmask_b32_e32 v145, v145, v245, vcc
.Lm16_nomask_s:
	v_max3_f32 v220, v114, v115, v116
	v_max3_f32 v220, v220, v117, v122
	v_max3_f32 v220, v220, v123, v124
	v_max3_f32 v220, v220, v125, v130
	v_max3_f32 v220, v220, v131, v132
	v_max3_f32 v220, v220, v133, v138
	v_max3_f32 v220, v220, v139, v140
	v_max_f32_e32 v220, v220, v141
	ds_bpermute_b32 v221, v246, v220
	s_waitcnt lgkmcnt(0)
	v_max_f32_e32 v220, v220, v221
	ds_bpermute_b32 v221, v247, v220
	s_waitcnt lgkmcnt(0)
	v_max_f32_e32 v220, v220, v221
	v_add_f32_e32 v220, 0x40e00000, v220
	v_max_f32_e32 v221, 0, v220
	v_add_f32_e32 v218, v218, v221
	v_exp_f32_e64 v222, -v221
	v_sub_f32_e32 v114, v114, v221
	v_sub_f32_e32 v115, v115, v221
	v_sub_f32_e32 v116, v116, v221
	v_sub_f32_e32 v117, v117, v221
	v_sub_f32_e32 v122, v122, v221
	v_sub_f32_e32 v123, v123, v221
	v_sub_f32_e32 v124, v124, v221
	v_sub_f32_e32 v125, v125, v221
	v_sub_f32_e32 v130, v130, v221
	v_sub_f32_e32 v131, v131, v221
	v_sub_f32_e32 v132, v132, v221
	v_sub_f32_e32 v133, v133, v221
	v_sub_f32_e32 v138, v138, v221
	v_sub_f32_e32 v139, v139, v221
	v_sub_f32_e32 v140, v140, v221
	v_sub_f32_e32 v141, v141, v221
	v_mul_f32_e32 v146, v146, v222
	v_mul_f32_e32 v147, v147, v222
	v_mul_f32_e32 v148, v148, v222
	v_mul_f32_e32 v149, v149, v222
	v_mul_f32_e32 v2, v2, v222
	v_mul_f32_e32 v3, v3, v222
	v_mul_f32_e32 v4, v4, v222
	v_mul_f32_e32 v5, v5, v222
	v_mul_f32_e32 v10, v10, v222
	v_mul_f32_e32 v11, v11, v222
	v_mul_f32_e32 v12, v12, v222
	v_mul_f32_e32 v13, v13, v222
	v_mul_f32_e32 v18, v18, v222
	v_mul_f32_e32 v19, v19, v222
	v_mul_f32_e32 v20, v20, v222
	v_mul_f32_e32 v21, v21, v222
	v_mul_f32_e32 v26, v26, v222
	v_mul_f32_e32 v27, v27, v222
	v_mul_f32_e32 v28, v28, v222
	v_mul_f32_e32 v29, v29, v222
	v_mul_f32_e32 v34, v34, v222
	v_mul_f32_e32 v35, v35, v222
	v_mul_f32_e32 v36, v36, v222
	v_mul_f32_e32 v37, v37, v222
	v_mul_f32_e32 v42, v42, v222
	v_mul_f32_e32 v43, v43, v222
	v_mul_f32_e32 v44, v44, v222
	v_mul_f32_e32 v45, v45, v222
	v_mul_f32_e32 v50, v50, v222
	v_mul_f32_e32 v51, v51, v222
	v_mul_f32_e32 v52, v52, v222
	v_mul_f32_e32 v53, v53, v222
	v_mul_f32_e32 v58, v58, v222
	v_mul_f32_e32 v59, v59, v222
	v_mul_f32_e32 v60, v60, v222
	v_mul_f32_e32 v61, v61, v222
	v_sub_f32_e32 v208, 0xc0e00000, v218
	v_sub_f32_e32 v209, 0xc0e00000, v218
	v_sub_f32_e32 v210, 0xc0e00000, v218
	v_sub_f32_e32 v211, 0xc0e00000, v218
	v_max3_f32 v220, v118, v119, v120
	v_max3_f32 v220, v220, v121, v126
	v_max3_f32 v220, v220, v127, v128
	v_max3_f32 v220, v220, v129, v134
	v_max3_f32 v220, v220, v135, v136
	v_max3_f32 v220, v220, v137, v142
	v_max3_f32 v220, v220, v143, v144
	v_max_f32_e32 v220, v220, v145
	ds_bpermute_b32 v221, v246, v220
	s_waitcnt lgkmcnt(0)
	v_max_f32_e32 v220, v220, v221
	ds_bpermute_b32 v221, v247, v220
	s_waitcnt lgkmcnt(0)
; __device__ __forceinline__ void partialSM_pre(f32x16& p0, f32x16& p1, float& m_reg, float& alpha) {
;     ...
;     { auto rr = __builtin_amdgcn_permlane32_swap(__float_as_uint(pmax), __float_as_uint(pmax), false, false);
;       pmax = fmaxf(__uint_as_float(rr[0]), __uint_as_float(rr[1])); }
;     if (__builtin_expect(__all(pmax <= THR2), 1)) { alpha = 1.f; }
;     else { const float d = fmaxf(pmax, 0.f); m_reg += d; alpha = __builtin_amdgcn_exp2f(-d);
; #pragma unroll
;         for (int r = 0; r < 16; ++r) { p0[r] -= d; p1[r] -= d; } }
; #pragma unroll
;     for (int r = 0; r < 16; ++r) p0[r] = __builtin_amdgcn_exp2f(p0[r]);
; }
; __device__ __forceinline__ void finishSM(f32x16& p0, f32x16& p1, float alpha, float& l_reg, bf16x8& pa0, bf16x8& pa1, bf16x8& pa2, bf16x8& pa3) {
; #pragma unroll
;     for (int r = 0; r < 16; ++r) p1[r] = __builtin_amdgcn_exp2f(p1[r]);
;     float ps = 0;
; #pragma unroll
;     for (int r = 0; r < 16; ++r) ps += p0[r];
; #pragma unroll
;     for (int r = 0; r < 16; ++r) ps += p1[r];
;     { auto rr = __builtin_amdgcn_permlane32_swap(__float_as_uint(ps), __float_as_uint(ps), false, false);
;       ps = __uint_as_float(rr[0]) + __uint_as_float(rr[1]); }
;     l_reg = l_reg * alpha + ps;
;     ...
;     PK4(p0, 0, pa0); PK4(p0, 8, pa1); PK4(p1, 0, pa2); PK4(p1, 8, pa3);
	v_max_f32_e32 v220, v220, v221
	v_add_f32_e32 v220, 0x40e00000, v220
	v_max_f32_e32 v221, 0, v220
	v_add_f32_e32 v219, v219, v221
	v_exp_f32_e64 v222, -v221
	v_sub_f32_e32 v118, v118, v221
	v_sub_f32_e32 v119, v119, v221
	v_sub_f32_e32 v120, v120, v221
	v_sub_f32_e32 v121, v121, v221
	v_sub_f32_e32 v126, v126, v221
	v_sub_f32_e32 v127, v127, v221
	v_sub_f32_e32 v128, v128, v221
	v_sub_f32_e32 v129, v129, v221
	v_sub_f32_e32 v134, v134, v221
	v_sub_f32_e32 v135, v135, v221
	v_sub_f32_e32 v136, v136, v221
	v_sub_f32_e32 v137, v137, v221
	v_sub_f32_e32 v142, v142, v221
	v_sub_f32_e32 v143, v143, v221
	v_sub_f32_e32 v144, v144, v221
	v_sub_f32_e32 v145, v145, v221
	v_mul_f32_e32 v150, v150, v222
	v_mul_f32_e32 v151, v151, v222
	v_mul_f32_e32 v152, v152, v222
	v_mul_f32_e32 v153, v153, v222
	v_mul_f32_e32 v6, v6, v222
	v_mul_f32_e32 v7, v7, v222
	v_mul_f32_e32 v8, v8, v222
	v_mul_f32_e32 v9, v9, v222
	v_mul_f32_e32 v14, v14, v222
	v_mul_f32_e32 v15, v15, v222
	v_mul_f32_e32 v16, v16, v222
	v_mul_f32_e32 v17, v17, v222
	v_mul_f32_e32 v22, v22, v222
	v_mul_f32_e32 v23, v23, v222
	v_mul_f32_e32 v24, v24, v222
	v_mul_f32_e32 v25, v25, v222
	v_mul_f32_e32 v30, v30, v222
	v_mul_f32_e32 v31, v31, v222
	v_mul_f32_e32 v32, v32, v222
	v_mul_f32_e32 v33, v33, v222
	v_mul_f32_e32 v38, v38, v222
	v_mul_f32_e32 v39, v39, v222
	v_mul_f32_e32 v40, v40, v222
	v_mul_f32_e32 v41, v41, v222
	v_mul_f32_e32 v46, v46, v222
	v_mul_f32_e32 v47, v47, v222
	v_mul_f32_e32 v48, v48, v222
	v_mul_f32_e32 v49, v49, v222
	v_mul_f32_e32 v54, v54, v222
	v_mul_f32_e32 v55, v55, v222
	v_mul_f32_e32 v56, v56, v222
	v_mul_f32_e32 v57, v57, v222
	v_mul_f32_e32 v62, v62, v222
	v_mul_f32_e32 v63, v63, v222
	v_mul_f32_e32 v64, v64, v222
	v_mul_f32_e32 v65, v65, v222
	v_sub_f32_e32 v212, 0xc0e00000, v219
	v_sub_f32_e32 v213, 0xc0e00000, v219
	v_sub_f32_e32 v214, 0xc0e00000, v219
	v_sub_f32_e32 v215, 0xc0e00000, v219
	v_exp_f32_e32 v114, v114
	v_exp_f32_e32 v115, v115
	v_exp_f32_e32 v116, v116
	v_exp_f32_e32 v117, v117
	v_exp_f32_e32 v118, v118
	v_exp_f32_e32 v119, v119
	v_exp_f32_e32 v120, v120
	v_exp_f32_e32 v121, v121
	v_exp_f32_e32 v122, v122
	v_exp_f32_e32 v123, v123
	v_exp_f32_e32 v124, v124
	v_exp_f32_e32 v125, v125
	v_exp_f32_e32 v126, v126
	v_exp_f32_e32 v127, v127
	v_exp_f32_e32 v128, v128
	v_exp_f32_e32 v129, v129
	v_exp_f32_e32 v130, v130
	v_exp_f32_e32 v131, v131
	v_exp_f32_e32 v132, v132
	v_exp_f32_e32 v133, v133
	v_exp_f32_e32 v134, v134
	v_exp_f32_e32 v135, v135
	v_exp_f32_e32 v136, v136
	v_exp_f32_e32 v137, v137
	v_exp_f32_e32 v138, v138
	v_exp_f32_e32 v139, v139
	v_exp_f32_e32 v140, v140
	v_exp_f32_e32 v141, v141
	v_exp_f32_e32 v142, v142
	v_exp_f32_e32 v143, v143
	v_exp_f32_e32 v144, v144
	v_exp_f32_e32 v145, v145
	v_cvt_pk_bf16_f32 v164, v114, v115
	v_cvt_pk_bf16_f32 v165, v116, v117
	v_cvt_pk_bf16_f32 v166, v122, v123
	v_cvt_pk_bf16_f32 v167, v124, v125
	v_cvt_pk_bf16_f32 v168, v130, v131
	v_cvt_pk_bf16_f32 v169, v132, v133
	v_cvt_pk_bf16_f32 v170, v138, v139
	v_cvt_pk_bf16_f32 v171, v140, v141
	v_cvt_pk_bf16_f32 v172, v118, v119
	v_cvt_pk_bf16_f32 v173, v120, v121
	v_cvt_pk_bf16_f32 v174, v126, v127
	v_cvt_pk_bf16_f32 v175, v128, v129
	v_cvt_pk_bf16_f32 v176, v134, v135
	v_cvt_pk_bf16_f32 v177, v136, v137
	v_cvt_pk_bf16_f32 v178, v142, v143
	v_cvt_pk_bf16_f32 v179, v144, v145
; #define PV_RD(S, d0) do { constexpr int b_ = (d0) * 512; TRRD(S##l0, b_); TRRD(S##h0, b_ + KS_ / 2); TRRD(S##l1, b_ + KS_); TRRD(S##h1, b_ + KS_ + KS_ / 2); TRRD(S##l2, b_ + 2 * KS_); TRRD(S##h2, b_ + 2 * KS_ + KS_ / 2); TRRD(S##l3, b_ + 3 * KS_); TRRD(S##h3, b_ + 3 * KS_ + KS_ / 2); } while (0)
; #define WL(n) do { asm volatile("s_waitcnt lgkmcnt(" #n ")" ::: "memory"); SBAR(); } while (0)
; template <int NCB> __device__ __forceinline__ void pv_tile(f32x16* o, int vb, bf16x8 pa0, bf16x8 pa1, bf16x8 pa2, bf16x8 pa3) {
;     ...
;     constexpr int KS_ = NCB * 1024;
;     ...
;     s16x4 Al0, Al1, Al2, Al3, Ah0, Ah1, Ah2, Ah3, Bl0, Bl1, Bl2, Bl3, Bh0, Bh1, Bh2, Bh3;
;     PV_RD(A, 0); PV_RD(B, 1); WL(8); PV_MM(A, 0);
;     if constexpr (NCB == 4) { PV_RD(A, 2); WL(8); PV_MM(B, 1); PV_RD(B, 3); WL(8); PV_MM(A, 2); WL(0); PV_MM(B, 3); }
;     else { WL(0); PV_MM(B, 1); }
.Lm16_pv:
	ds_read_b64_tr_b16 v[180:181], v230 offset:0
	ds_read_b64_tr_b16 v[182:183], v230 offset:4096
	ds_read_b64_tr_b16 v[184:185], v230 offset:8192
	ds_read_b64_tr_b16 v[186:187], v230 offset:12288
	ds_read_b64_tr_b16 v[188:189], v231 offset:0
	ds_read_b64_tr_b16 v[190:191], v231 offset:4096
	ds_read_b64_tr_b16 v[192:193], v231 offset:8192
	ds_read_b64_tr_b16 v[194:195], v231 offset:12288
	s_waitcnt lgkmcnt(6)
	v_mfma_f32_16x16x32_bf16 v[2:5], v[180:183], v[164:167], v[2:5]
	v_mfma_f32_16x16x32_bf16 v[6:9], v[180:183], v[172:175], v[6:9]
	v_mfma_f32_16x16x32_bf16 v[146:149], v[154:157], v[164:167], v[146:149]
	v_mfma_f32_16x16x32_bf16 v[150:153], v[154:157], v[172:175], v[150:153]
	ds_read_b64_tr_b16 v[180:181], v230 offset:512
	ds_read_b64_tr_b16 v[182:183], v230 offset:4608
	s_waitcnt lgkmcnt(6)
	v_mfma_f32_16x16x32_bf16 v[2:5], v[184:187], v[168:171], v[2:5]
	v_mfma_f32_16x16x32_bf16 v[6:9], v[184:187], v[176:179], v[6:9]
	v_mfma_f32_16x16x32_bf16 v[146:149], v[154:157], v[168:171], v[146:149]
	v_mfma_f32_16x16x32_bf16 v[150:153], v[154:157], v[176:179], v[150:153]
	ds_read_b64_tr_b16 v[184:185], v230 offset:8704
	ds_read_b64_tr_b16 v[186:187], v230 offset:12800
	s_waitcnt lgkmcnt(6)
	v_mfma_f32_16x16x32_bf16 v[10:13], v[188:191], v[164:167], v[10:13]
	v_mfma_f32_16x16x32_bf16 v[14:17], v[188:191], v[172:175], v[14:17]
	ds_read_b64_tr_b16 v[188:189], v231 offset:512
	ds_read_b64_tr_b16 v[190:191], v231 offset:4608
	s_waitcnt lgkmcnt(6)
	v_mfma_f32_16x16x32_bf16 v[10:13], v[192:195], v[168:171], v[10:13]
	v_mfma_f32_16x16x32_bf16 v[14:17], v[192:195], v[176:179], v[14:17]
	ds_read_b64_tr_b16 v[192:193], v231 offset:8704
	ds_read_b64_tr_b16 v[194:195], v231 offset:12800
	s_waitcnt lgkmcnt(6)
	v_mfma_f32_16x16x32_bf16 v[18:21], v[180:183], v[164:167], v[18:21]
	v_mfma_f32_16x16x32_bf16 v[22:25], v[180:183], v[172:175], v[22:25]
	ds_read_b64_tr_b16 v[180:181], v230 offset:1024
	ds_read_b64_tr_b16 v[182:183], v230 offset:5120
	s_waitcnt lgkmcnt(6)
	v_mfma_f32_16x16x32_bf16 v[18:21], v[184:187], v[168:171], v[18:21]
	v_mfma_f32_16x16x32_bf16 v[22:25], v[184:187], v[176:179], v[22:25]
	ds_read_b64_tr_b16 v[184:185], v230 offset:9216
	ds_read_b64_tr_b16 v[186:187], v230 offset:13312
	s_waitcnt lgkmcnt(6)
	v_mfma_f32_16x16x32_bf16 v[26:29], v[188:191], v[164:167], v[26:29]
	v_mfma_f32_16x16x32_bf16 v[30:33], v[188:191], v[172:175], v[30:33]
	ds_read_b64_tr_b16 v[188:189], v231 offset:1024
	ds_read_b64_tr_b16 v[190:191], v231 offset:5120
	s_waitcnt lgkmcnt(6)
	v_mfma_f32_16x16x32_bf16 v[26:29], v[192:195], v[168:171], v[26:29]
	v_mfma_f32_16x16x32_bf16 v[30:33], v[192:195], v[176:179], v[30:33]
	ds_read_b64_tr_b16 v[192:193], v231 offset:9216
	ds_read_b64_tr_b16 v[194:195], v231 offset:13312
	s_waitcnt lgkmcnt(6)
	v_mfma_f32_16x16x32_bf16 v[34:37], v[180:183], v[164:167], v[34:37]
	v_mfma_f32_16x16x32_bf16 v[38:41], v[180:183], v[172:175], v[38:41]
	ds_read_b64_tr_b16 v[180:181], v230 offset:1536
	ds_read_b64_tr_b16 v[182:183], v230 offset:5632
	s_waitcnt lgkmcnt(6)
	v_mfma_f32_16x16x32_bf16 v[34:37], v[184:187], v[168:171], v[34:37]
	v_mfma_f32_16x16x32_bf16 v[38:41], v[184:187], v[176:179], v[38:41]
	ds_read_b64_tr_b16 v[184:185], v230 offset:9728
	ds_read_b64_tr_b16 v[186:187], v230 offset:13824
	s_waitcnt lgkmcnt(6)
	v_mfma_f32_16x16x32_bf16 v[42:45], v[188:191], v[164:167], v[42:45]
	v_mfma_f32_16x16x32_bf16 v[46:49], v[188:191], v[172:175], v[46:49]
	ds_read_b64_tr_b16 v[188:189], v231 offset:1536
	ds_read_b64_tr_b16 v[190:191], v231 offset:5632
	s_waitcnt lgkmcnt(6)
	v_mfma_f32_16x16x32_bf16 v[42:45], v[192:195], v[168:171], v[42:45]
	v_mfma_f32_16x16x32_bf16 v[46:49], v[192:195], v[176:179], v[46:49]
	ds_read_b64_tr_b16 v[192:193], v231 offset:9728
	ds_read_b64_tr_b16 v[194:195], v231 offset:13824
	s_waitcnt lgkmcnt(6)
	v_mfma_f32_16x16x32_bf16 v[50:53], v[180:183], v[164:167], v[50:53]
	v_mfma_f32_16x16x32_bf16 v[54:57], v[180:183], v[172:175], v[54:57]
	s_waitcnt lgkmcnt(4)
	v_mfma_f32_16x16x32_bf16 v[50:53], v[184:187], v[168:171], v[50:53]
	v_mfma_f32_16x16x32_bf16 v[54:57], v[184:187], v[176:179], v[54:57]
	s_waitcnt lgkmcnt(2)
	v_mfma_f32_16x16x32_bf16 v[58:61], v[188:191], v[164:167], v[58:61]
	v_mfma_f32_16x16x32_bf16 v[62:65], v[188:191], v[172:175], v[62:65]
	s_waitcnt lgkmcnt(0)
	v_mfma_f32_16x16x32_bf16 v[58:61], v[192:195], v[168:171], v[58:61]
	v_mfma_f32_16x16x32_bf16 v[62:65], v[192:195], v[176:179], v[62:65]
